# in-proj epilogue (forget-gate slices): the 16 lower-bound row loads (4 distinct) fetched once at the epilogue head instead of load+wait in place
# speedup vs baseline: 1.0276x; 1.0027x over previous
.LBB0_192:
	s_lshr_b32 s33, s10, 1
	s_cmp_eq_u32 s33, 10
	s_cselect_b64 s[4:5], -1, 0
	s_and_b32 s0, s10, 0x7c
	s_cmp_lg_u32 s0, 20
	s_cselect_b64 s[34:35], -1, 0
	s_and_b32 s1, s10, 0x76
	s_cmp_lg_u32 s1, 18
	s_cselect_b64 s[56:57], -1, 0
	s_cmp_eq_u32 s0, 8
	s_cselect_b64 s[10:11], -1, 0
	s_and_b32 s0, s22, 0x80
	s_waitcnt vmcnt(7)
	v_or_b32_e32 v77, s0, v149
	s_lshl_b32 s0, s33, 10
	s_add_u32 s0, s38, s0
	s_addc_u32 s1, s39, 0
	s_add_u32 s12, s0, 0x10f000
	s_addc_u32 s13, s1, 0
	s_andn2_b64 vcc, exec, s[10:11]
	s_cbranch_vccnz .Lg0_nolb
	v_lshlrev_b32_e32 v2, 2, v77
	global_load_dwordx4 v[116:119], v2, s[12:13]
	global_load_dwordx4 v[120:123], v2, s[12:13] offset:64
	global_load_dwordx4 v[124:127], v2, s[12:13] offset:128
	global_load_dwordx4 v[128:131], v2, s[12:13] offset:192
.Lg0_nolb:
	s_mov_b64 s[0:1], -1
	s_and_b64 vcc, exec, s[34:35]
	s_cbranch_vccz .LBB0_254
	s_and_b64 vcc, exec, s[56:57]
	s_cbranch_vccz .LBB0_206
	s_mov_b64 s[58:59], -1
	s_mov_b64 s[0:1], 0
	s_cmp_lt_i32 s33, 6
	s_cbranch_scc1 .LBB0_201
	s_cmp_gt_i32 s33, 7
	s_mov_b64 s[6:7], 0
	s_cbranch_scc0 .LBB0_198
	s_cmp_eq_u32 s33, 8
	s_mov_b64 s[6:7], -1
	s_cbranch_scc0 .LBB0_471
	v_mul_f32_e32 v2, 0xbfb8aa3b, v64
	v_exp_f32_e32 v2, v2
	v_mul_f32_e32 v68, 0xbfb8aa3b, v65
	v_exp_f32_e32 v68, v68
	v_mul_f32_e32 v70, 0xbfb8aa3b, v67
	v_add_f32_e32 v2, 1.0, v2
	v_exp_f32_e32 v71, v70
	v_add_f32_e32 v69, 1.0, v68
	v_rcp_f32_e32 v68, v2
	v_mul_f32_e32 v2, 0xbfb8aa3b, v66
	v_exp_f32_e32 v2, v2
	v_rcp_f32_e32 v69, v69
	s_mov_b64 s[6:7], 0
	s_mov_b64 s[58:59], 0
	v_add_f32_e32 v2, 1.0, v2
	v_rcp_f32_e32 v70, v2
	v_add_f32_e32 v2, 1.0, v71
	v_rcp_f32_e32 v71, v2

.LBB0_203:
	s_andn2_b64 vcc, exec, s[6:7]
	s_cbranch_vccnz .LBB0_206
	s_andn2_b64 vcc, exec, s[10:11]
	s_cbranch_vccnz .LBB0_455
	v_lshlrev_b32_e32 v2, 2, v77
	s_waitcnt vmcnt(0)
	v_mov_b32_e32 v68, v116
	v_mov_b32_e32 v69, v117
	v_mov_b32_e32 v70, v118
	v_mov_b32_e32 v71, v119
	s_waitcnt vmcnt(6)
	v_mul_f32_e32 v72, 0xbfb8aa3b, v64
	v_exp_f32_e32 v72, v72
	s_mov_b32 s6, 0x3f317217
	v_add_f32_e32 v72, 1.0, v72
	v_rcp_f32_e32 v72, v72
	s_waitcnt vmcnt(0)
	v_max_f32_e32 v2, v68, v68
	v_max_f32_e32 v2, 0xda24260, v2
	v_sub_f32_e32 v68, 1.0, v68
	v_fmac_f32_e32 v2, v72, v68
	v_cmp_gt_f32_e32 vcc, s19, v2
	v_mul_f32_e32 v72, 0xbfb8aa3b, v65
	v_exp_f32_e32 v72, v72
	v_cndmask_b32_e64 v68, 0, 32, vcc
	v_ldexp_f32 v2, v2, v68
	v_log_f32_e32 v2, v2
	v_add_f32_e32 v72, 1.0, v72
	v_rcp_f32_e32 v72, v72
	v_mul_f32_e32 v68, 0x3f317217, v2
	v_fma_f32 v68, v2, s6, -v68
	v_fmac_f32_e32 v68, 0x3377d1cf, v2
	v_fmac_f32_e32 v68, 0x3f317217, v2
	v_cmp_lt_f32_e64 s[0:1], |v2|, s37
	s_nop 1
	v_cndmask_b32_e64 v2, v2, v68, s[0:1]
	v_cndmask_b32_e32 v68, 0, v230, vcc
	v_sub_f32_e32 v68, v2, v68
	v_max_f32_e32 v2, v69, v69
	v_max_f32_e32 v2, 0xda24260, v2
	v_sub_f32_e32 v69, 1.0, v69
	v_fmac_f32_e32 v2, v72, v69
	v_cmp_gt_f32_e32 vcc, s19, v2
	v_mul_f32_e32 v72, 0xbfb8aa3b, v66
	v_exp_f32_e32 v72, v72
	v_cndmask_b32_e64 v69, 0, 32, vcc
	v_ldexp_f32 v2, v2, v69
	v_log_f32_e32 v2, v2
	v_add_f32_e32 v72, 1.0, v72
	v_rcp_f32_e32 v72, v72
	v_mul_f32_e32 v69, 0x3f317217, v2
	v_fma_f32 v69, v2, s6, -v69
	v_fmac_f32_e32 v69, 0x3377d1cf, v2
	v_fmac_f32_e32 v69, 0x3f317217, v2
	v_cmp_lt_f32_e64 s[0:1], |v2|, s37
	s_nop 1
	v_cndmask_b32_e64 v2, v2, v69, s[0:1]
	v_cndmask_b32_e32 v69, 0, v230, vcc
	v_sub_f32_e32 v69, v2, v69
	v_max_f32_e32 v2, v70, v70
	v_max_f32_e32 v2, 0xda24260, v2
	v_sub_f32_e32 v70, 1.0, v70
	v_fmac_f32_e32 v2, v72, v70
	v_cmp_gt_f32_e32 vcc, s19, v2
	v_mul_f32_e32 v72, 0xbfb8aa3b, v67
	v_exp_f32_e32 v72, v72
	v_cndmask_b32_e64 v70, 0, 32, vcc
	v_ldexp_f32 v2, v2, v70
	v_log_f32_e32 v2, v2
	v_add_f32_e32 v72, 1.0, v72
	v_rcp_f32_e32 v72, v72
	v_mul_f32_e32 v70, 0x3f317217, v2
	v_fma_f32 v70, v2, s6, -v70
	v_fmac_f32_e32 v70, 0x3377d1cf, v2
	v_fmac_f32_e32 v70, 0x3f317217, v2
	v_cmp_lt_f32_e64 s[0:1], |v2|, s37
	s_nop 1
	v_cndmask_b32_e64 v2, v2, v70, s[0:1]
	v_cndmask_b32_e32 v70, 0, v230, vcc
	v_sub_f32_e32 v70, v2, v70
	v_max_f32_e32 v2, v71, v71
	v_max_f32_e32 v2, 0xda24260, v2
	v_sub_f32_e32 v71, 1.0, v71
	v_fmac_f32_e32 v2, v72, v71
	v_cmp_gt_f32_e32 vcc, s19, v2
	s_nop 1
	v_cndmask_b32_e64 v71, 0, 32, vcc
	v_ldexp_f32 v2, v2, v71
	v_log_f32_e32 v2, v2
	s_nop 0
	v_mul_f32_e32 v71, 0x3f317217, v2
	v_fma_f32 v71, v2, s6, -v71
	v_fmac_f32_e32 v71, 0x3377d1cf, v2
	v_fmac_f32_e32 v71, 0x3f317217, v2
	v_cmp_lt_f32_e64 s[0:1], |v2|, s37
	s_nop 1
	v_cndmask_b32_e64 v2, v2, v71, s[0:1]
	v_cndmask_b32_e32 v71, 0, v230, vcc
	v_sub_f32_e32 v71, v2, v71
	s_mov_b64 s[0:1], 0

.LBB0_218:
	s_andn2_b64 vcc, exec, s[58:59]
	s_cbranch_vccnz .LBB0_221
	s_andn2_b64 vcc, exec, s[10:11]
	s_cbranch_vccnz .LBB0_456
	v_lshlrev_b32_e32 v68, 2, v77
	s_waitcnt vmcnt(0)
	v_mov_b32_e32 v68, v120
	v_mov_b32_e32 v69, v121
	v_mov_b32_e32 v70, v122
	v_mov_b32_e32 v71, v123
	s_waitcnt vmcnt(6)
	v_mul_f32_e32 v73, 0xbfb8aa3b, v60
	v_exp_f32_e32 v73, v73
	s_mov_b32 s43, 0x3f317217
	v_add_f32_e32 v73, 1.0, v73
	v_rcp_f32_e32 v73, v73
	s_waitcnt vmcnt(0)
	v_max_f32_e32 v72, v68, v68
	v_max_f32_e32 v72, 0xda24260, v72
	v_sub_f32_e32 v68, 1.0, v68
	v_fmac_f32_e32 v72, v73, v68
	v_cmp_gt_f32_e32 vcc, s19, v72
	v_mul_f32_e32 v73, 0xbfb8aa3b, v61
	v_exp_f32_e32 v73, v73
	v_cndmask_b32_e64 v68, 0, 32, vcc
	v_ldexp_f32 v68, v72, v68
	v_log_f32_e32 v68, v68
	v_add_f32_e32 v73, 1.0, v73
	v_rcp_f32_e32 v73, v73
	v_mul_f32_e32 v72, 0x3f317217, v68
	v_fma_f32 v72, v68, s43, -v72
	v_fmac_f32_e32 v72, 0x3377d1cf, v68
	v_fmac_f32_e32 v72, 0x3f317217, v68
	v_cmp_lt_f32_e64 s[0:1], |v68|, s37
	s_nop 1
	v_cndmask_b32_e64 v68, v68, v72, s[0:1]
	v_cndmask_b32_e32 v72, 0, v230, vcc
	v_sub_f32_e32 v68, v68, v72
	v_max_f32_e32 v72, v69, v69
	v_max_f32_e32 v72, 0xda24260, v72
	v_sub_f32_e32 v69, 1.0, v69
	v_fmac_f32_e32 v72, v73, v69
	v_cmp_gt_f32_e32 vcc, s19, v72
	v_mul_f32_e32 v73, 0xbfb8aa3b, v62
	v_exp_f32_e32 v73, v73
	v_cndmask_b32_e64 v69, 0, 32, vcc
	v_ldexp_f32 v69, v72, v69
	v_log_f32_e32 v69, v69
	v_add_f32_e32 v73, 1.0, v73
	v_rcp_f32_e32 v73, v73
	v_mul_f32_e32 v72, 0x3f317217, v69
	v_fma_f32 v72, v69, s43, -v72
	v_fmac_f32_e32 v72, 0x3377d1cf, v69
	v_fmac_f32_e32 v72, 0x3f317217, v69
	v_cmp_lt_f32_e64 s[0:1], |v69|, s37
	s_nop 1
	v_cndmask_b32_e64 v69, v69, v72, s[0:1]
	v_cndmask_b32_e32 v72, 0, v230, vcc
	v_sub_f32_e32 v69, v69, v72
	v_max_f32_e32 v72, v70, v70
	v_max_f32_e32 v72, 0xda24260, v72
	v_sub_f32_e32 v70, 1.0, v70
	v_fmac_f32_e32 v72, v73, v70
	v_cmp_gt_f32_e32 vcc, s19, v72
	v_mul_f32_e32 v73, 0xbfb8aa3b, v63
	v_exp_f32_e32 v73, v73
	v_cndmask_b32_e64 v70, 0, 32, vcc
	v_ldexp_f32 v70, v72, v70
	v_log_f32_e32 v70, v70
	v_add_f32_e32 v73, 1.0, v73
	v_rcp_f32_e32 v73, v73
	v_mul_f32_e32 v72, 0x3f317217, v70
	v_fma_f32 v72, v70, s43, -v72
	v_fmac_f32_e32 v72, 0x3377d1cf, v70
	v_fmac_f32_e32 v72, 0x3f317217, v70
	v_cmp_lt_f32_e64 s[0:1], |v70|, s37
	s_nop 1
	v_cndmask_b32_e64 v70, v70, v72, s[0:1]
	v_cndmask_b32_e32 v72, 0, v230, vcc
	v_sub_f32_e32 v70, v70, v72
	v_max_f32_e32 v72, v71, v71
	v_max_f32_e32 v72, 0xda24260, v72
	v_sub_f32_e32 v71, 1.0, v71
	v_fmac_f32_e32 v72, v73, v71
	v_cmp_gt_f32_e32 vcc, s19, v72
	s_nop 1
	v_cndmask_b32_e64 v71, 0, 32, vcc
	v_ldexp_f32 v71, v72, v71
	v_log_f32_e32 v71, v71
	s_nop 0
	v_mul_f32_e32 v72, 0x3f317217, v71
	v_fma_f32 v72, v71, s43, -v72
	v_fmac_f32_e32 v72, 0x3377d1cf, v71
	v_fmac_f32_e32 v72, 0x3f317217, v71
	v_cmp_lt_f32_e64 s[0:1], |v71|, s37
	s_nop 1
	v_cndmask_b32_e64 v71, v71, v72, s[0:1]
	v_cndmask_b32_e32 v72, 0, v230, vcc
	v_sub_f32_e32 v71, v71, v72
	s_mov_b64 s[0:1], 0

.LBB0_233:
	s_andn2_b64 vcc, exec, s[58:59]
	s_cbranch_vccnz .LBB0_236
	s_andn2_b64 vcc, exec, s[10:11]
	s_cbranch_vccnz .LBB0_457
	v_lshlrev_b32_e32 v68, 2, v77
	s_waitcnt vmcnt(0)
	v_mov_b32_e32 v68, v124
	v_mov_b32_e32 v69, v125
	v_mov_b32_e32 v70, v126
	v_mov_b32_e32 v71, v127
	s_waitcnt vmcnt(6)
	v_mul_f32_e32 v73, 0xbfb8aa3b, v56
	v_exp_f32_e32 v73, v73
	s_mov_b32 s43, 0x3f317217
	v_add_f32_e32 v73, 1.0, v73
	v_rcp_f32_e32 v73, v73
	s_waitcnt vmcnt(0)
	v_max_f32_e32 v72, v68, v68
	v_max_f32_e32 v72, 0xda24260, v72
	v_sub_f32_e32 v68, 1.0, v68
	v_fmac_f32_e32 v72, v73, v68
	v_cmp_gt_f32_e32 vcc, s19, v72
	v_mul_f32_e32 v73, 0xbfb8aa3b, v57
	v_exp_f32_e32 v73, v73
	v_cndmask_b32_e64 v68, 0, 32, vcc
	v_ldexp_f32 v68, v72, v68
	v_log_f32_e32 v68, v68
	v_add_f32_e32 v73, 1.0, v73
	v_rcp_f32_e32 v73, v73
	v_mul_f32_e32 v72, 0x3f317217, v68
	v_fma_f32 v72, v68, s43, -v72
	v_fmac_f32_e32 v72, 0x3377d1cf, v68
	v_fmac_f32_e32 v72, 0x3f317217, v68
	v_cmp_lt_f32_e64 s[0:1], |v68|, s37
	s_nop 1
	v_cndmask_b32_e64 v68, v68, v72, s[0:1]
	v_cndmask_b32_e32 v72, 0, v230, vcc
	v_sub_f32_e32 v68, v68, v72
	v_max_f32_e32 v72, v69, v69
	v_max_f32_e32 v72, 0xda24260, v72
	v_sub_f32_e32 v69, 1.0, v69
	v_fmac_f32_e32 v72, v73, v69
	v_cmp_gt_f32_e32 vcc, s19, v72
	v_mul_f32_e32 v73, 0xbfb8aa3b, v58
	v_exp_f32_e32 v73, v73
	v_cndmask_b32_e64 v69, 0, 32, vcc
	v_ldexp_f32 v69, v72, v69
	v_log_f32_e32 v69, v69
	v_add_f32_e32 v73, 1.0, v73
	v_rcp_f32_e32 v73, v73
	v_mul_f32_e32 v72, 0x3f317217, v69
	v_fma_f32 v72, v69, s43, -v72
	v_fmac_f32_e32 v72, 0x3377d1cf, v69
	v_fmac_f32_e32 v72, 0x3f317217, v69
	v_cmp_lt_f32_e64 s[0:1], |v69|, s37
	s_nop 1
	v_cndmask_b32_e64 v69, v69, v72, s[0:1]
	v_cndmask_b32_e32 v72, 0, v230, vcc
	v_sub_f32_e32 v69, v69, v72
	v_max_f32_e32 v72, v70, v70
	v_max_f32_e32 v72, 0xda24260, v72
	v_sub_f32_e32 v70, 1.0, v70
	v_fmac_f32_e32 v72, v73, v70
	v_cmp_gt_f32_e32 vcc, s19, v72
	v_mul_f32_e32 v73, 0xbfb8aa3b, v59
	v_exp_f32_e32 v73, v73
	v_cndmask_b32_e64 v70, 0, 32, vcc
	v_ldexp_f32 v70, v72, v70
	v_log_f32_e32 v70, v70
	v_add_f32_e32 v73, 1.0, v73
	v_rcp_f32_e32 v73, v73
	v_mul_f32_e32 v72, 0x3f317217, v70
	v_fma_f32 v72, v70, s43, -v72
	v_fmac_f32_e32 v72, 0x3377d1cf, v70
	v_fmac_f32_e32 v72, 0x3f317217, v70
	v_cmp_lt_f32_e64 s[0:1], |v70|, s37
	s_nop 1
	v_cndmask_b32_e64 v70, v70, v72, s[0:1]
	v_cndmask_b32_e32 v72, 0, v230, vcc
	v_sub_f32_e32 v70, v70, v72
	v_max_f32_e32 v72, v71, v71
	v_max_f32_e32 v72, 0xda24260, v72
	v_sub_f32_e32 v71, 1.0, v71
	v_fmac_f32_e32 v72, v73, v71
	v_cmp_gt_f32_e32 vcc, s19, v72
	s_nop 1
	v_cndmask_b32_e64 v71, 0, 32, vcc
	v_ldexp_f32 v71, v72, v71
	v_log_f32_e32 v71, v71
	s_nop 0
	v_mul_f32_e32 v72, 0x3f317217, v71
	v_fma_f32 v72, v71, s43, -v72
	v_fmac_f32_e32 v72, 0x3377d1cf, v71
	v_fmac_f32_e32 v72, 0x3f317217, v71
	v_cmp_lt_f32_e64 s[0:1], |v71|, s37
	s_nop 1
	v_cndmask_b32_e64 v71, v71, v72, s[0:1]
	v_cndmask_b32_e32 v72, 0, v230, vcc
	v_sub_f32_e32 v71, v71, v72
	s_mov_b64 s[0:1], 0

.LBB0_248:
	s_andn2_b64 vcc, exec, s[6:7]
	s_cbranch_vccnz .LBB0_251
	s_andn2_b64 vcc, exec, s[10:11]
	s_cbranch_vccnz .LBB0_458
	v_lshlrev_b32_e32 v2, 2, v77
	s_waitcnt vmcnt(0)
	v_mov_b32_e32 v68, v128
	v_mov_b32_e32 v69, v129
	v_mov_b32_e32 v70, v130
	v_mov_b32_e32 v71, v131
	s_waitcnt vmcnt(6)
	v_mul_f32_e32 v72, 0xbfb8aa3b, v52
	v_exp_f32_e32 v72, v72
	s_mov_b32 s6, 0x3f317217
	v_add_f32_e32 v72, 1.0, v72
	v_rcp_f32_e32 v72, v72
	s_waitcnt vmcnt(0)
	v_max_f32_e32 v2, v68, v68
	v_max_f32_e32 v2, 0xda24260, v2
	v_sub_f32_e32 v68, 1.0, v68
	v_fmac_f32_e32 v2, v72, v68
	v_cmp_gt_f32_e32 vcc, s19, v2
	v_mul_f32_e32 v72, 0xbfb8aa3b, v53
	v_exp_f32_e32 v72, v72
	v_cndmask_b32_e64 v68, 0, 32, vcc
	v_ldexp_f32 v2, v2, v68
	v_log_f32_e32 v2, v2
	v_add_f32_e32 v72, 1.0, v72
	v_rcp_f32_e32 v72, v72
	v_mul_f32_e32 v68, 0x3f317217, v2
	v_fma_f32 v68, v2, s6, -v68
	v_fmac_f32_e32 v68, 0x3377d1cf, v2
	v_fmac_f32_e32 v68, 0x3f317217, v2
	v_cmp_lt_f32_e64 s[0:1], |v2|, s37
	s_nop 1
	v_cndmask_b32_e64 v2, v2, v68, s[0:1]
	v_cndmask_b32_e32 v68, 0, v230, vcc
	v_sub_f32_e32 v68, v2, v68
	v_max_f32_e32 v2, v69, v69
	v_max_f32_e32 v2, 0xda24260, v2
	v_sub_f32_e32 v69, 1.0, v69
	v_fmac_f32_e32 v2, v72, v69
	v_cmp_gt_f32_e32 vcc, s19, v2
	v_mul_f32_e32 v72, 0xbfb8aa3b, v54
	v_exp_f32_e32 v72, v72
	v_cndmask_b32_e64 v69, 0, 32, vcc
	v_ldexp_f32 v2, v2, v69
	v_log_f32_e32 v2, v2
	v_add_f32_e32 v72, 1.0, v72
	v_rcp_f32_e32 v72, v72
	v_mul_f32_e32 v69, 0x3f317217, v2
	v_fma_f32 v69, v2, s6, -v69
	v_fmac_f32_e32 v69, 0x3377d1cf, v2
	v_fmac_f32_e32 v69, 0x3f317217, v2
	v_cmp_lt_f32_e64 s[0:1], |v2|, s37
	s_nop 1
	v_cndmask_b32_e64 v2, v2, v69, s[0:1]
	v_cndmask_b32_e32 v69, 0, v230, vcc
	v_sub_f32_e32 v69, v2, v69
	v_max_f32_e32 v2, v70, v70
	v_max_f32_e32 v2, 0xda24260, v2
	v_sub_f32_e32 v70, 1.0, v70
	v_fmac_f32_e32 v2, v72, v70
	v_cmp_gt_f32_e32 vcc, s19, v2
	v_mul_f32_e32 v72, 0xbfb8aa3b, v55
	v_exp_f32_e32 v72, v72
	v_cndmask_b32_e64 v70, 0, 32, vcc
	v_ldexp_f32 v2, v2, v70
	v_log_f32_e32 v2, v2
	v_add_f32_e32 v72, 1.0, v72
	v_rcp_f32_e32 v72, v72
	v_mul_f32_e32 v70, 0x3f317217, v2
	v_fma_f32 v70, v2, s6, -v70
	v_fmac_f32_e32 v70, 0x3377d1cf, v2
	v_fmac_f32_e32 v70, 0x3f317217, v2
	v_cmp_lt_f32_e64 s[0:1], |v2|, s37
	s_nop 1
	v_cndmask_b32_e64 v2, v2, v70, s[0:1]
	v_cndmask_b32_e32 v70, 0, v230, vcc
	v_sub_f32_e32 v70, v2, v70
	v_max_f32_e32 v2, v71, v71
	v_max_f32_e32 v2, 0xda24260, v2
	v_sub_f32_e32 v71, 1.0, v71
	v_fmac_f32_e32 v2, v72, v71
	v_cmp_gt_f32_e32 vcc, s19, v2
	s_nop 1
	v_cndmask_b32_e64 v71, 0, 32, vcc
	v_ldexp_f32 v2, v2, v71
	v_log_f32_e32 v2, v2
	s_nop 0
	v_mul_f32_e32 v71, 0x3f317217, v2
	v_fma_f32 v71, v2, s6, -v71
	v_fmac_f32_e32 v71, 0x3377d1cf, v2
	v_fmac_f32_e32 v71, 0x3f317217, v2
	v_cmp_lt_f32_e64 s[0:1], |v2|, s37
	s_nop 1
	v_cndmask_b32_e64 v2, v2, v71, s[0:1]
	v_cndmask_b32_e32 v71, 0, v230, vcc
	v_sub_f32_e32 v71, v2, v71
	s_mov_b64 s[0:1], 0

.LBB0_269:
	s_andn2_b64 vcc, exec, s[34:35]
	s_cbranch_vccnz .LBB0_272
	s_andn2_b64 vcc, exec, s[10:11]
	s_cbranch_vccnz .LBB0_459
	v_lshlrev_b32_e32 v2, 2, v77
	s_waitcnt vmcnt(0)
	v_mov_b32_e32 v52, v116
	v_mov_b32_e32 v53, v117
	v_mov_b32_e32 v54, v118
	v_mov_b32_e32 v55, v119
	v_mul_f32_e32 v56, 0xbfb8aa3b, v48
	v_exp_f32_e32 v56, v56
	s_mov_b32 s34, 0x3f317217
	v_add_f32_e32 v56, 1.0, v56
	v_rcp_f32_e32 v56, v56
	s_waitcnt vmcnt(0)
	v_max_f32_e32 v2, v52, v52
	v_max_f32_e32 v2, 0xda24260, v2
	v_sub_f32_e32 v52, 1.0, v52
	v_fmac_f32_e32 v2, v56, v52
	v_cmp_gt_f32_e32 vcc, s19, v2
	v_mul_f32_e32 v56, 0xbfb8aa3b, v49
	v_exp_f32_e32 v56, v56
	v_cndmask_b32_e64 v52, 0, 32, vcc
	v_ldexp_f32 v2, v2, v52
	v_log_f32_e32 v2, v2
	v_add_f32_e32 v56, 1.0, v56
	v_rcp_f32_e32 v56, v56
	v_mul_f32_e32 v52, 0x3f317217, v2
	v_fma_f32 v52, v2, s34, -v52
	v_fmac_f32_e32 v52, 0x3377d1cf, v2
	v_fmac_f32_e32 v52, 0x3f317217, v2
	v_cmp_lt_f32_e64 s[0:1], |v2|, s37
	s_nop 1
	v_cndmask_b32_e64 v2, v2, v52, s[0:1]
	v_cndmask_b32_e32 v52, 0, v230, vcc
	v_sub_f32_e32 v52, v2, v52
	v_max_f32_e32 v2, v53, v53
	v_max_f32_e32 v2, 0xda24260, v2
	v_sub_f32_e32 v53, 1.0, v53
	v_fmac_f32_e32 v2, v56, v53
	v_cmp_gt_f32_e32 vcc, s19, v2
	v_mul_f32_e32 v56, 0xbfb8aa3b, v50
	v_exp_f32_e32 v56, v56
	v_cndmask_b32_e64 v53, 0, 32, vcc
	v_ldexp_f32 v2, v2, v53
	v_log_f32_e32 v2, v2
	v_add_f32_e32 v56, 1.0, v56
	v_rcp_f32_e32 v56, v56
	v_mul_f32_e32 v53, 0x3f317217, v2
	v_fma_f32 v53, v2, s34, -v53
	v_fmac_f32_e32 v53, 0x3377d1cf, v2
	v_fmac_f32_e32 v53, 0x3f317217, v2
	v_cmp_lt_f32_e64 s[0:1], |v2|, s37
	s_nop 1
	v_cndmask_b32_e64 v2, v2, v53, s[0:1]
	v_cndmask_b32_e32 v53, 0, v230, vcc
	v_sub_f32_e32 v53, v2, v53
	v_max_f32_e32 v2, v54, v54
	v_max_f32_e32 v2, 0xda24260, v2
	v_sub_f32_e32 v54, 1.0, v54
	v_fmac_f32_e32 v2, v56, v54
	v_cmp_gt_f32_e32 vcc, s19, v2
	v_mul_f32_e32 v56, 0xbfb8aa3b, v51
	v_exp_f32_e32 v56, v56
	v_cndmask_b32_e64 v54, 0, 32, vcc
	v_ldexp_f32 v2, v2, v54
	v_log_f32_e32 v2, v2
	v_add_f32_e32 v56, 1.0, v56
	v_rcp_f32_e32 v56, v56
	v_mul_f32_e32 v54, 0x3f317217, v2
	v_fma_f32 v54, v2, s34, -v54
	v_fmac_f32_e32 v54, 0x3377d1cf, v2
	v_fmac_f32_e32 v54, 0x3f317217, v2
	v_cmp_lt_f32_e64 s[0:1], |v2|, s37
	s_nop 1
	v_cndmask_b32_e64 v2, v2, v54, s[0:1]
	v_cndmask_b32_e32 v54, 0, v230, vcc
	v_sub_f32_e32 v54, v2, v54
	v_max_f32_e32 v2, v55, v55
	v_max_f32_e32 v2, 0xda24260, v2
	v_sub_f32_e32 v55, 1.0, v55
	v_fmac_f32_e32 v2, v56, v55
	v_cmp_gt_f32_e32 vcc, s19, v2
	s_nop 1
	v_cndmask_b32_e64 v55, 0, 32, vcc
	v_ldexp_f32 v2, v2, v55
	v_log_f32_e32 v2, v2
	s_nop 0
	v_mul_f32_e32 v55, 0x3f317217, v2
	v_fma_f32 v55, v2, s34, -v55
	v_fmac_f32_e32 v55, 0x3377d1cf, v2
	v_fmac_f32_e32 v55, 0x3f317217, v2
	v_cmp_lt_f32_e64 s[0:1], |v2|, s37
	s_nop 1
	v_cndmask_b32_e64 v2, v2, v55, s[0:1]
	v_cndmask_b32_e32 v55, 0, v230, vcc
	v_sub_f32_e32 v55, v2, v55
	s_mov_b64 s[0:1], 0

.LBB0_284:
	s_andn2_b64 vcc, exec, s[34:35]
	s_cbranch_vccnz .LBB0_287
	s_andn2_b64 vcc, exec, s[10:11]
	s_cbranch_vccnz .LBB0_460
	v_lshlrev_b32_e32 v2, 2, v77
	s_waitcnt vmcnt(0)
	v_mov_b32_e32 v52, v120
	v_mov_b32_e32 v53, v121
	v_mov_b32_e32 v54, v122
	v_mov_b32_e32 v55, v123
	v_mul_f32_e32 v56, 0xbfb8aa3b, v44
	v_exp_f32_e32 v56, v56
	s_mov_b32 s34, 0x3f317217
	v_add_f32_e32 v56, 1.0, v56
	v_rcp_f32_e32 v56, v56
	s_waitcnt vmcnt(0)
	v_max_f32_e32 v2, v52, v52
	v_max_f32_e32 v2, 0xda24260, v2
	v_sub_f32_e32 v52, 1.0, v52
	v_fmac_f32_e32 v2, v56, v52
	v_cmp_gt_f32_e32 vcc, s19, v2
	v_mul_f32_e32 v56, 0xbfb8aa3b, v45
	v_exp_f32_e32 v56, v56
	v_cndmask_b32_e64 v52, 0, 32, vcc
	v_ldexp_f32 v2, v2, v52
	v_log_f32_e32 v2, v2
	v_add_f32_e32 v56, 1.0, v56
	v_rcp_f32_e32 v56, v56
	v_mul_f32_e32 v52, 0x3f317217, v2
	v_fma_f32 v52, v2, s34, -v52
	v_fmac_f32_e32 v52, 0x3377d1cf, v2
	v_fmac_f32_e32 v52, 0x3f317217, v2
	v_cmp_lt_f32_e64 s[0:1], |v2|, s37
	s_nop 1
	v_cndmask_b32_e64 v2, v2, v52, s[0:1]
	v_cndmask_b32_e32 v52, 0, v230, vcc
	v_sub_f32_e32 v52, v2, v52
	v_max_f32_e32 v2, v53, v53
	v_max_f32_e32 v2, 0xda24260, v2
	v_sub_f32_e32 v53, 1.0, v53
	v_fmac_f32_e32 v2, v56, v53
	v_cmp_gt_f32_e32 vcc, s19, v2
	v_mul_f32_e32 v56, 0xbfb8aa3b, v46
	v_exp_f32_e32 v56, v56
	v_cndmask_b32_e64 v53, 0, 32, vcc
	v_ldexp_f32 v2, v2, v53
	v_log_f32_e32 v2, v2
	v_add_f32_e32 v56, 1.0, v56
	v_rcp_f32_e32 v56, v56
	v_mul_f32_e32 v53, 0x3f317217, v2
	v_fma_f32 v53, v2, s34, -v53
	v_fmac_f32_e32 v53, 0x3377d1cf, v2
	v_fmac_f32_e32 v53, 0x3f317217, v2
	v_cmp_lt_f32_e64 s[0:1], |v2|, s37
	s_nop 1
	v_cndmask_b32_e64 v2, v2, v53, s[0:1]
	v_cndmask_b32_e32 v53, 0, v230, vcc
	v_sub_f32_e32 v53, v2, v53
	v_max_f32_e32 v2, v54, v54
	v_max_f32_e32 v2, 0xda24260, v2
	v_sub_f32_e32 v54, 1.0, v54
	v_fmac_f32_e32 v2, v56, v54
	v_cmp_gt_f32_e32 vcc, s19, v2
	v_mul_f32_e32 v56, 0xbfb8aa3b, v47
	v_exp_f32_e32 v56, v56
	v_cndmask_b32_e64 v54, 0, 32, vcc
	v_ldexp_f32 v2, v2, v54
	v_log_f32_e32 v2, v2
	v_add_f32_e32 v56, 1.0, v56
	v_rcp_f32_e32 v56, v56
	v_mul_f32_e32 v54, 0x3f317217, v2
	v_fma_f32 v54, v2, s34, -v54
	v_fmac_f32_e32 v54, 0x3377d1cf, v2
	v_fmac_f32_e32 v54, 0x3f317217, v2
	v_cmp_lt_f32_e64 s[0:1], |v2|, s37
	s_nop 1
	v_cndmask_b32_e64 v2, v2, v54, s[0:1]
	v_cndmask_b32_e32 v54, 0, v230, vcc
	v_sub_f32_e32 v54, v2, v54
	v_max_f32_e32 v2, v55, v55
	v_max_f32_e32 v2, 0xda24260, v2
	v_sub_f32_e32 v55, 1.0, v55
	v_fmac_f32_e32 v2, v56, v55
	v_cmp_gt_f32_e32 vcc, s19, v2
	s_nop 1
	v_cndmask_b32_e64 v55, 0, 32, vcc
	v_ldexp_f32 v2, v2, v55
	v_log_f32_e32 v2, v2
	s_nop 0
	v_mul_f32_e32 v55, 0x3f317217, v2
	v_fma_f32 v55, v2, s34, -v55
	v_fmac_f32_e32 v55, 0x3377d1cf, v2
	v_fmac_f32_e32 v55, 0x3f317217, v2
	v_cmp_lt_f32_e64 s[0:1], |v2|, s37
	s_nop 1
	v_cndmask_b32_e64 v2, v2, v55, s[0:1]
	v_cndmask_b32_e32 v55, 0, v230, vcc
	v_sub_f32_e32 v55, v2, v55
	s_mov_b64 s[0:1], 0

.LBB0_299:
	s_andn2_b64 vcc, exec, s[34:35]
	s_cbranch_vccnz .LBB0_302
	s_andn2_b64 vcc, exec, s[10:11]
	s_cbranch_vccnz .LBB0_461
	v_lshlrev_b32_e32 v2, 2, v77
	s_waitcnt vmcnt(0)
	v_mov_b32_e32 v52, v124
	v_mov_b32_e32 v53, v125
	v_mov_b32_e32 v54, v126
	v_mov_b32_e32 v55, v127
	v_mul_f32_e32 v56, 0xbfb8aa3b, v40
	v_exp_f32_e32 v56, v56
	s_mov_b32 s34, 0x3f317217
	v_add_f32_e32 v56, 1.0, v56
	v_rcp_f32_e32 v56, v56
	s_waitcnt vmcnt(0)
	v_max_f32_e32 v2, v52, v52
	v_max_f32_e32 v2, 0xda24260, v2
	v_sub_f32_e32 v52, 1.0, v52
	v_fmac_f32_e32 v2, v56, v52
	v_cmp_gt_f32_e32 vcc, s19, v2
	v_mul_f32_e32 v56, 0xbfb8aa3b, v41
	v_exp_f32_e32 v56, v56
	v_cndmask_b32_e64 v52, 0, 32, vcc
	v_ldexp_f32 v2, v2, v52
	v_log_f32_e32 v2, v2
	v_add_f32_e32 v56, 1.0, v56
	v_rcp_f32_e32 v56, v56
	v_mul_f32_e32 v52, 0x3f317217, v2
	v_fma_f32 v52, v2, s34, -v52
	v_fmac_f32_e32 v52, 0x3377d1cf, v2
	v_fmac_f32_e32 v52, 0x3f317217, v2
	v_cmp_lt_f32_e64 s[0:1], |v2|, s37
	s_nop 1
	v_cndmask_b32_e64 v2, v2, v52, s[0:1]
	v_cndmask_b32_e32 v52, 0, v230, vcc
	v_sub_f32_e32 v52, v2, v52
	v_max_f32_e32 v2, v53, v53
	v_max_f32_e32 v2, 0xda24260, v2
	v_sub_f32_e32 v53, 1.0, v53
	v_fmac_f32_e32 v2, v56, v53
	v_cmp_gt_f32_e32 vcc, s19, v2
	v_mul_f32_e32 v56, 0xbfb8aa3b, v42
	v_exp_f32_e32 v56, v56
	v_cndmask_b32_e64 v53, 0, 32, vcc
	v_ldexp_f32 v2, v2, v53
	v_log_f32_e32 v2, v2
	v_add_f32_e32 v56, 1.0, v56
	v_rcp_f32_e32 v56, v56
	v_mul_f32_e32 v53, 0x3f317217, v2
	v_fma_f32 v53, v2, s34, -v53
	v_fmac_f32_e32 v53, 0x3377d1cf, v2
	v_fmac_f32_e32 v53, 0x3f317217, v2
	v_cmp_lt_f32_e64 s[0:1], |v2|, s37
	s_nop 1
	v_cndmask_b32_e64 v2, v2, v53, s[0:1]
	v_cndmask_b32_e32 v53, 0, v230, vcc
	v_sub_f32_e32 v53, v2, v53
	v_max_f32_e32 v2, v54, v54
	v_max_f32_e32 v2, 0xda24260, v2
	v_sub_f32_e32 v54, 1.0, v54
	v_fmac_f32_e32 v2, v56, v54
	v_cmp_gt_f32_e32 vcc, s19, v2
	v_mul_f32_e32 v56, 0xbfb8aa3b, v43
	v_exp_f32_e32 v56, v56
	v_cndmask_b32_e64 v54, 0, 32, vcc
	v_ldexp_f32 v2, v2, v54
	v_log_f32_e32 v2, v2
	v_add_f32_e32 v56, 1.0, v56
	v_rcp_f32_e32 v56, v56
	v_mul_f32_e32 v54, 0x3f317217, v2
	v_fma_f32 v54, v2, s34, -v54
	v_fmac_f32_e32 v54, 0x3377d1cf, v2
	v_fmac_f32_e32 v54, 0x3f317217, v2
	v_cmp_lt_f32_e64 s[0:1], |v2|, s37
	s_nop 1
	v_cndmask_b32_e64 v2, v2, v54, s[0:1]
	v_cndmask_b32_e32 v54, 0, v230, vcc
	v_sub_f32_e32 v54, v2, v54
	v_max_f32_e32 v2, v55, v55
	v_max_f32_e32 v2, 0xda24260, v2
	v_sub_f32_e32 v55, 1.0, v55
	v_fmac_f32_e32 v2, v56, v55
	v_cmp_gt_f32_e32 vcc, s19, v2
	s_nop 1
	v_cndmask_b32_e64 v55, 0, 32, vcc
	v_ldexp_f32 v2, v2, v55
	v_log_f32_e32 v2, v2
	s_nop 0
	v_mul_f32_e32 v55, 0x3f317217, v2
	v_fma_f32 v55, v2, s34, -v55
	v_fmac_f32_e32 v55, 0x3377d1cf, v2
	v_fmac_f32_e32 v55, 0x3f317217, v2
	v_cmp_lt_f32_e64 s[0:1], |v2|, s37
	s_nop 1
	v_cndmask_b32_e64 v2, v2, v55, s[0:1]
	v_cndmask_b32_e32 v55, 0, v230, vcc
	v_sub_f32_e32 v55, v2, v55
	s_mov_b64 s[0:1], 0

.LBB0_314:
	s_andn2_b64 vcc, exec, s[34:35]
	s_cbranch_vccnz .LBB0_317
	s_andn2_b64 vcc, exec, s[10:11]
	s_cbranch_vccnz .LBB0_462
	v_lshlrev_b32_e32 v2, 2, v77
	s_waitcnt vmcnt(0)
	v_mov_b32_e32 v52, v128
	v_mov_b32_e32 v53, v129
	v_mov_b32_e32 v54, v130
	v_mov_b32_e32 v55, v131
	v_mul_f32_e32 v56, 0xbfb8aa3b, v36
	v_exp_f32_e32 v56, v56
	s_mov_b32 s34, 0x3f317217
	v_add_f32_e32 v56, 1.0, v56
	v_rcp_f32_e32 v56, v56
	s_waitcnt vmcnt(0)
	v_max_f32_e32 v2, v52, v52
	v_max_f32_e32 v2, 0xda24260, v2
	v_sub_f32_e32 v52, 1.0, v52
	v_fmac_f32_e32 v2, v56, v52
	v_cmp_gt_f32_e32 vcc, s19, v2
	v_mul_f32_e32 v56, 0xbfb8aa3b, v37
	v_exp_f32_e32 v56, v56
	v_cndmask_b32_e64 v52, 0, 32, vcc
	v_ldexp_f32 v2, v2, v52
	v_log_f32_e32 v2, v2
	v_add_f32_e32 v56, 1.0, v56
	v_rcp_f32_e32 v56, v56
	v_mul_f32_e32 v52, 0x3f317217, v2
	v_fma_f32 v52, v2, s34, -v52
	v_fmac_f32_e32 v52, 0x3377d1cf, v2
	v_fmac_f32_e32 v52, 0x3f317217, v2
	v_cmp_lt_f32_e64 s[0:1], |v2|, s37
	s_nop 1
	v_cndmask_b32_e64 v2, v2, v52, s[0:1]
	v_cndmask_b32_e32 v52, 0, v230, vcc
	v_sub_f32_e32 v52, v2, v52
	v_max_f32_e32 v2, v53, v53
	v_max_f32_e32 v2, 0xda24260, v2
	v_sub_f32_e32 v53, 1.0, v53
	v_fmac_f32_e32 v2, v56, v53
	v_cmp_gt_f32_e32 vcc, s19, v2
	v_mul_f32_e32 v56, 0xbfb8aa3b, v38
	v_exp_f32_e32 v56, v56
	v_cndmask_b32_e64 v53, 0, 32, vcc
	v_ldexp_f32 v2, v2, v53
	v_log_f32_e32 v2, v2
	v_add_f32_e32 v56, 1.0, v56
	v_rcp_f32_e32 v56, v56
	v_mul_f32_e32 v53, 0x3f317217, v2
	v_fma_f32 v53, v2, s34, -v53
	v_fmac_f32_e32 v53, 0x3377d1cf, v2
	v_fmac_f32_e32 v53, 0x3f317217, v2
	v_cmp_lt_f32_e64 s[0:1], |v2|, s37
	s_nop 1
	v_cndmask_b32_e64 v2, v2, v53, s[0:1]
	v_cndmask_b32_e32 v53, 0, v230, vcc
	v_sub_f32_e32 v53, v2, v53
	v_max_f32_e32 v2, v54, v54
	v_max_f32_e32 v2, 0xda24260, v2
	v_sub_f32_e32 v54, 1.0, v54
	v_fmac_f32_e32 v2, v56, v54
	v_cmp_gt_f32_e32 vcc, s19, v2
	v_mul_f32_e32 v56, 0xbfb8aa3b, v39
	v_exp_f32_e32 v56, v56
	v_cndmask_b32_e64 v54, 0, 32, vcc
	v_ldexp_f32 v2, v2, v54
	v_log_f32_e32 v2, v2
	v_add_f32_e32 v56, 1.0, v56
	v_rcp_f32_e32 v56, v56
	v_mul_f32_e32 v54, 0x3f317217, v2
	v_fma_f32 v54, v2, s34, -v54
	v_fmac_f32_e32 v54, 0x3377d1cf, v2
	v_fmac_f32_e32 v54, 0x3f317217, v2
	v_cmp_lt_f32_e64 s[0:1], |v2|, s37
	s_nop 1
	v_cndmask_b32_e64 v2, v2, v54, s[0:1]
	v_cndmask_b32_e32 v54, 0, v230, vcc
	v_sub_f32_e32 v54, v2, v54
	v_max_f32_e32 v2, v55, v55
	v_max_f32_e32 v2, 0xda24260, v2
	v_sub_f32_e32 v55, 1.0, v55
	v_fmac_f32_e32 v2, v56, v55
	v_cmp_gt_f32_e32 vcc, s19, v2
	s_nop 1
	v_cndmask_b32_e64 v55, 0, 32, vcc
	v_ldexp_f32 v2, v2, v55
	v_log_f32_e32 v2, v2
	s_nop 0
	v_mul_f32_e32 v55, 0x3f317217, v2
	v_fma_f32 v55, v2, s34, -v55
	v_fmac_f32_e32 v55, 0x3377d1cf, v2
	v_fmac_f32_e32 v55, 0x3f317217, v2
	v_cmp_lt_f32_e64 s[0:1], |v2|, s37
	s_nop 1
	v_cndmask_b32_e64 v2, v2, v55, s[0:1]
	v_cndmask_b32_e32 v55, 0, v230, vcc
	v_sub_f32_e32 v55, v2, v55
	s_mov_b64 s[0:1], 0

.LBB0_335:
	s_andn2_b64 vcc, exec, s[34:35]
	s_cbranch_vccnz .LBB0_338
	s_andn2_b64 vcc, exec, s[10:11]
	s_cbranch_vccnz .LBB0_463
	v_lshlrev_b32_e32 v2, 2, v77
	s_waitcnt vmcnt(0)
	v_mov_b32_e32 v36, v116
	v_mov_b32_e32 v37, v117
	v_mov_b32_e32 v38, v118
	v_mov_b32_e32 v39, v119
	v_mul_f32_e32 v40, 0xbfb8aa3b, v32
	v_exp_f32_e32 v40, v40
	s_mov_b32 s34, 0x3f317217
	v_add_f32_e32 v40, 1.0, v40
	v_rcp_f32_e32 v40, v40
	s_waitcnt vmcnt(0)
	v_max_f32_e32 v2, v36, v36
	v_max_f32_e32 v2, 0xda24260, v2
	v_sub_f32_e32 v36, 1.0, v36
	v_fmac_f32_e32 v2, v40, v36
	v_cmp_gt_f32_e32 vcc, s19, v2
	v_mul_f32_e32 v40, 0xbfb8aa3b, v33
	v_exp_f32_e32 v40, v40
	v_cndmask_b32_e64 v36, 0, 32, vcc
	v_ldexp_f32 v2, v2, v36
	v_log_f32_e32 v2, v2
	v_add_f32_e32 v40, 1.0, v40
	v_rcp_f32_e32 v40, v40
	v_mul_f32_e32 v36, 0x3f317217, v2
	v_fma_f32 v36, v2, s34, -v36
	v_fmac_f32_e32 v36, 0x3377d1cf, v2
	v_fmac_f32_e32 v36, 0x3f317217, v2
	v_cmp_lt_f32_e64 s[0:1], |v2|, s37
	s_nop 1
	v_cndmask_b32_e64 v2, v2, v36, s[0:1]
	v_cndmask_b32_e32 v36, 0, v230, vcc
	v_sub_f32_e32 v36, v2, v36
	v_max_f32_e32 v2, v37, v37
	v_max_f32_e32 v2, 0xda24260, v2
	v_sub_f32_e32 v37, 1.0, v37
	v_fmac_f32_e32 v2, v40, v37
	v_cmp_gt_f32_e32 vcc, s19, v2
	v_mul_f32_e32 v40, 0xbfb8aa3b, v34
	v_exp_f32_e32 v40, v40
	v_cndmask_b32_e64 v37, 0, 32, vcc
	v_ldexp_f32 v2, v2, v37
	v_log_f32_e32 v2, v2
	v_add_f32_e32 v40, 1.0, v40
	v_rcp_f32_e32 v40, v40
	v_mul_f32_e32 v37, 0x3f317217, v2
	v_fma_f32 v37, v2, s34, -v37
	v_fmac_f32_e32 v37, 0x3377d1cf, v2
	v_fmac_f32_e32 v37, 0x3f317217, v2
	v_cmp_lt_f32_e64 s[0:1], |v2|, s37
	s_nop 1
	v_cndmask_b32_e64 v2, v2, v37, s[0:1]
	v_cndmask_b32_e32 v37, 0, v230, vcc
	v_sub_f32_e32 v37, v2, v37
	v_max_f32_e32 v2, v38, v38
	v_max_f32_e32 v2, 0xda24260, v2
	v_sub_f32_e32 v38, 1.0, v38
	v_fmac_f32_e32 v2, v40, v38
	v_cmp_gt_f32_e32 vcc, s19, v2
	v_mul_f32_e32 v40, 0xbfb8aa3b, v35
	v_exp_f32_e32 v40, v40
	v_cndmask_b32_e64 v38, 0, 32, vcc
	v_ldexp_f32 v2, v2, v38
	v_log_f32_e32 v2, v2
	v_add_f32_e32 v40, 1.0, v40
	v_rcp_f32_e32 v40, v40
	v_mul_f32_e32 v38, 0x3f317217, v2
	v_fma_f32 v38, v2, s34, -v38
	v_fmac_f32_e32 v38, 0x3377d1cf, v2
	v_fmac_f32_e32 v38, 0x3f317217, v2
	v_cmp_lt_f32_e64 s[0:1], |v2|, s37
	s_nop 1
	v_cndmask_b32_e64 v2, v2, v38, s[0:1]
	v_cndmask_b32_e32 v38, 0, v230, vcc
	v_sub_f32_e32 v38, v2, v38
	v_max_f32_e32 v2, v39, v39
	v_max_f32_e32 v2, 0xda24260, v2
	v_sub_f32_e32 v39, 1.0, v39
	v_fmac_f32_e32 v2, v40, v39
	v_cmp_gt_f32_e32 vcc, s19, v2
	s_nop 1
	v_cndmask_b32_e64 v39, 0, 32, vcc
	v_ldexp_f32 v2, v2, v39
	v_log_f32_e32 v2, v2
	s_nop 0
	v_mul_f32_e32 v39, 0x3f317217, v2
	v_fma_f32 v39, v2, s34, -v39
	v_fmac_f32_e32 v39, 0x3377d1cf, v2
	v_fmac_f32_e32 v39, 0x3f317217, v2
	v_cmp_lt_f32_e64 s[0:1], |v2|, s37
	s_nop 1
	v_cndmask_b32_e64 v2, v2, v39, s[0:1]
	v_cndmask_b32_e32 v39, 0, v230, vcc
	v_sub_f32_e32 v39, v2, v39
	s_mov_b64 s[0:1], 0

.LBB0_350:
	s_andn2_b64 vcc, exec, s[34:35]
	s_cbranch_vccnz .LBB0_353
	s_andn2_b64 vcc, exec, s[10:11]
	s_cbranch_vccnz .LBB0_464
	v_lshlrev_b32_e32 v2, 2, v77
	s_waitcnt vmcnt(0)
	v_mov_b32_e32 v36, v120
	v_mov_b32_e32 v37, v121
	v_mov_b32_e32 v38, v122
	v_mov_b32_e32 v39, v123
	v_mul_f32_e32 v40, 0xbfb8aa3b, v28
	v_exp_f32_e32 v40, v40
	s_mov_b32 s34, 0x3f317217
	v_add_f32_e32 v40, 1.0, v40
	v_rcp_f32_e32 v40, v40
	s_waitcnt vmcnt(0)
	v_max_f32_e32 v2, v36, v36
	v_max_f32_e32 v2, 0xda24260, v2
	v_sub_f32_e32 v36, 1.0, v36
	v_fmac_f32_e32 v2, v40, v36
	v_cmp_gt_f32_e32 vcc, s19, v2
	v_mul_f32_e32 v40, 0xbfb8aa3b, v29
	v_exp_f32_e32 v40, v40
	v_cndmask_b32_e64 v36, 0, 32, vcc
	v_ldexp_f32 v2, v2, v36
	v_log_f32_e32 v2, v2
	v_add_f32_e32 v40, 1.0, v40
	v_rcp_f32_e32 v40, v40
	v_mul_f32_e32 v36, 0x3f317217, v2
	v_fma_f32 v36, v2, s34, -v36
	v_fmac_f32_e32 v36, 0x3377d1cf, v2
	v_fmac_f32_e32 v36, 0x3f317217, v2
	v_cmp_lt_f32_e64 s[0:1], |v2|, s37
	s_nop 1
	v_cndmask_b32_e64 v2, v2, v36, s[0:1]
	v_cndmask_b32_e32 v36, 0, v230, vcc
	v_sub_f32_e32 v36, v2, v36
	v_max_f32_e32 v2, v37, v37
	v_max_f32_e32 v2, 0xda24260, v2
	v_sub_f32_e32 v37, 1.0, v37
	v_fmac_f32_e32 v2, v40, v37
	v_cmp_gt_f32_e32 vcc, s19, v2
	v_mul_f32_e32 v40, 0xbfb8aa3b, v30
	v_exp_f32_e32 v40, v40
	v_cndmask_b32_e64 v37, 0, 32, vcc
	v_ldexp_f32 v2, v2, v37
	v_log_f32_e32 v2, v2
	v_add_f32_e32 v40, 1.0, v40
	v_rcp_f32_e32 v40, v40
	v_mul_f32_e32 v37, 0x3f317217, v2
	v_fma_f32 v37, v2, s34, -v37
	v_fmac_f32_e32 v37, 0x3377d1cf, v2
	v_fmac_f32_e32 v37, 0x3f317217, v2
	v_cmp_lt_f32_e64 s[0:1], |v2|, s37
	s_nop 1
	v_cndmask_b32_e64 v2, v2, v37, s[0:1]
	v_cndmask_b32_e32 v37, 0, v230, vcc
	v_sub_f32_e32 v37, v2, v37
	v_max_f32_e32 v2, v38, v38
	v_max_f32_e32 v2, 0xda24260, v2
	v_sub_f32_e32 v38, 1.0, v38
	v_fmac_f32_e32 v2, v40, v38
	v_cmp_gt_f32_e32 vcc, s19, v2
	v_mul_f32_e32 v40, 0xbfb8aa3b, v31
	v_exp_f32_e32 v40, v40
	v_cndmask_b32_e64 v38, 0, 32, vcc
	v_ldexp_f32 v2, v2, v38
	v_log_f32_e32 v2, v2
	v_add_f32_e32 v40, 1.0, v40
	v_rcp_f32_e32 v40, v40
	v_mul_f32_e32 v38, 0x3f317217, v2
	v_fma_f32 v38, v2, s34, -v38
	v_fmac_f32_e32 v38, 0x3377d1cf, v2
	v_fmac_f32_e32 v38, 0x3f317217, v2
	v_cmp_lt_f32_e64 s[0:1], |v2|, s37
	s_nop 1
	v_cndmask_b32_e64 v2, v2, v38, s[0:1]
	v_cndmask_b32_e32 v38, 0, v230, vcc
	v_sub_f32_e32 v38, v2, v38
	v_max_f32_e32 v2, v39, v39
	v_max_f32_e32 v2, 0xda24260, v2
	v_sub_f32_e32 v39, 1.0, v39
	v_fmac_f32_e32 v2, v40, v39
	v_cmp_gt_f32_e32 vcc, s19, v2
	s_nop 1
	v_cndmask_b32_e64 v39, 0, 32, vcc
	v_ldexp_f32 v2, v2, v39
	v_log_f32_e32 v2, v2
	s_nop 0
	v_mul_f32_e32 v39, 0x3f317217, v2
	v_fma_f32 v39, v2, s34, -v39
	v_fmac_f32_e32 v39, 0x3377d1cf, v2
	v_fmac_f32_e32 v39, 0x3f317217, v2
	v_cmp_lt_f32_e64 s[0:1], |v2|, s37
	s_nop 1
	v_cndmask_b32_e64 v2, v2, v39, s[0:1]
	v_cndmask_b32_e32 v39, 0, v230, vcc
	v_sub_f32_e32 v39, v2, v39
	s_mov_b64 s[0:1], 0

.LBB0_365:
	s_andn2_b64 vcc, exec, s[34:35]
	s_cbranch_vccnz .LBB0_368
	s_andn2_b64 vcc, exec, s[10:11]
	s_cbranch_vccnz .LBB0_465
	v_lshlrev_b32_e32 v2, 2, v77
	s_waitcnt vmcnt(0)
	v_mov_b32_e32 v36, v124
	v_mov_b32_e32 v37, v125
	v_mov_b32_e32 v38, v126
	v_mov_b32_e32 v39, v127
	v_mul_f32_e32 v40, 0xbfb8aa3b, v24
	v_exp_f32_e32 v40, v40
	s_mov_b32 s34, 0x3f317217
	v_add_f32_e32 v40, 1.0, v40
	v_rcp_f32_e32 v40, v40
	s_waitcnt vmcnt(0)
	v_max_f32_e32 v2, v36, v36
	v_max_f32_e32 v2, 0xda24260, v2
	v_sub_f32_e32 v36, 1.0, v36
	v_fmac_f32_e32 v2, v40, v36
	v_cmp_gt_f32_e32 vcc, s19, v2
	v_mul_f32_e32 v40, 0xbfb8aa3b, v25
	v_exp_f32_e32 v40, v40
	v_cndmask_b32_e64 v36, 0, 32, vcc
	v_ldexp_f32 v2, v2, v36
	v_log_f32_e32 v2, v2
	v_add_f32_e32 v40, 1.0, v40
	v_rcp_f32_e32 v40, v40
	v_mul_f32_e32 v36, 0x3f317217, v2
	v_fma_f32 v36, v2, s34, -v36
	v_fmac_f32_e32 v36, 0x3377d1cf, v2
	v_fmac_f32_e32 v36, 0x3f317217, v2
	v_cmp_lt_f32_e64 s[0:1], |v2|, s37
	s_nop 1
	v_cndmask_b32_e64 v2, v2, v36, s[0:1]
	v_cndmask_b32_e32 v36, 0, v230, vcc
	v_sub_f32_e32 v36, v2, v36
	v_max_f32_e32 v2, v37, v37
	v_max_f32_e32 v2, 0xda24260, v2
	v_sub_f32_e32 v37, 1.0, v37
	v_fmac_f32_e32 v2, v40, v37
	v_cmp_gt_f32_e32 vcc, s19, v2
	v_mul_f32_e32 v40, 0xbfb8aa3b, v26
	v_exp_f32_e32 v40, v40
	v_cndmask_b32_e64 v37, 0, 32, vcc
	v_ldexp_f32 v2, v2, v37
	v_log_f32_e32 v2, v2
	v_add_f32_e32 v40, 1.0, v40
	v_rcp_f32_e32 v40, v40
	v_mul_f32_e32 v37, 0x3f317217, v2
	v_fma_f32 v37, v2, s34, -v37
	v_fmac_f32_e32 v37, 0x3377d1cf, v2
	v_fmac_f32_e32 v37, 0x3f317217, v2
	v_cmp_lt_f32_e64 s[0:1], |v2|, s37
	s_nop 1
	v_cndmask_b32_e64 v2, v2, v37, s[0:1]
	v_cndmask_b32_e32 v37, 0, v230, vcc
	v_sub_f32_e32 v37, v2, v37
	v_max_f32_e32 v2, v38, v38
	v_max_f32_e32 v2, 0xda24260, v2
	v_sub_f32_e32 v38, 1.0, v38
	v_fmac_f32_e32 v2, v40, v38
	v_cmp_gt_f32_e32 vcc, s19, v2
	v_mul_f32_e32 v40, 0xbfb8aa3b, v27
	v_exp_f32_e32 v40, v40
	v_cndmask_b32_e64 v38, 0, 32, vcc
	v_ldexp_f32 v2, v2, v38
	v_log_f32_e32 v2, v2
	v_add_f32_e32 v40, 1.0, v40
	v_rcp_f32_e32 v40, v40
	v_mul_f32_e32 v38, 0x3f317217, v2
	v_fma_f32 v38, v2, s34, -v38
	v_fmac_f32_e32 v38, 0x3377d1cf, v2
	v_fmac_f32_e32 v38, 0x3f317217, v2
	v_cmp_lt_f32_e64 s[0:1], |v2|, s37
	s_nop 1
	v_cndmask_b32_e64 v2, v2, v38, s[0:1]
	v_cndmask_b32_e32 v38, 0, v230, vcc
	v_sub_f32_e32 v38, v2, v38
	v_max_f32_e32 v2, v39, v39
	v_max_f32_e32 v2, 0xda24260, v2
	v_sub_f32_e32 v39, 1.0, v39
	v_fmac_f32_e32 v2, v40, v39
	v_cmp_gt_f32_e32 vcc, s19, v2
	s_nop 1
	v_cndmask_b32_e64 v39, 0, 32, vcc
	v_ldexp_f32 v2, v2, v39
	v_log_f32_e32 v2, v2
	s_nop 0
	v_mul_f32_e32 v39, 0x3f317217, v2
	v_fma_f32 v39, v2, s34, -v39
	v_fmac_f32_e32 v39, 0x3377d1cf, v2
	v_fmac_f32_e32 v39, 0x3f317217, v2
	v_cmp_lt_f32_e64 s[0:1], |v2|, s37
	s_nop 1
	v_cndmask_b32_e64 v2, v2, v39, s[0:1]
	v_cndmask_b32_e32 v39, 0, v230, vcc
	v_sub_f32_e32 v39, v2, v39
	s_mov_b64 s[0:1], 0

.LBB0_380:
	s_andn2_b64 vcc, exec, s[34:35]
	s_cbranch_vccnz .LBB0_383
	s_andn2_b64 vcc, exec, s[10:11]
	s_cbranch_vccnz .LBB0_466
	v_lshlrev_b32_e32 v2, 2, v77
	s_waitcnt vmcnt(0)
	v_mov_b32_e32 v36, v128
	v_mov_b32_e32 v37, v129
	v_mov_b32_e32 v38, v130
	v_mov_b32_e32 v39, v131
	v_mul_f32_e32 v40, 0xbfb8aa3b, v20
	v_exp_f32_e32 v40, v40
	s_mov_b32 s34, 0x3f317217
	v_add_f32_e32 v40, 1.0, v40
	v_rcp_f32_e32 v40, v40
	s_waitcnt vmcnt(0)
	v_max_f32_e32 v2, v36, v36
	v_max_f32_e32 v2, 0xda24260, v2
	v_sub_f32_e32 v36, 1.0, v36
	v_fmac_f32_e32 v2, v40, v36
	v_cmp_gt_f32_e32 vcc, s19, v2
	v_mul_f32_e32 v40, 0xbfb8aa3b, v21
	v_exp_f32_e32 v40, v40
	v_cndmask_b32_e64 v36, 0, 32, vcc
	v_ldexp_f32 v2, v2, v36
	v_log_f32_e32 v2, v2
	v_add_f32_e32 v40, 1.0, v40
	v_rcp_f32_e32 v40, v40
	v_mul_f32_e32 v36, 0x3f317217, v2
	v_fma_f32 v36, v2, s34, -v36
	v_fmac_f32_e32 v36, 0x3377d1cf, v2
	v_fmac_f32_e32 v36, 0x3f317217, v2
	v_cmp_lt_f32_e64 s[0:1], |v2|, s37
	s_nop 1
	v_cndmask_b32_e64 v2, v2, v36, s[0:1]
	v_cndmask_b32_e32 v36, 0, v230, vcc
	v_sub_f32_e32 v36, v2, v36
	v_max_f32_e32 v2, v37, v37
	v_max_f32_e32 v2, 0xda24260, v2
	v_sub_f32_e32 v37, 1.0, v37
	v_fmac_f32_e32 v2, v40, v37
	v_cmp_gt_f32_e32 vcc, s19, v2
	v_mul_f32_e32 v40, 0xbfb8aa3b, v22
	v_exp_f32_e32 v40, v40
	v_cndmask_b32_e64 v37, 0, 32, vcc
	v_ldexp_f32 v2, v2, v37
	v_log_f32_e32 v2, v2
	v_add_f32_e32 v40, 1.0, v40
	v_rcp_f32_e32 v40, v40
	v_mul_f32_e32 v37, 0x3f317217, v2
	v_fma_f32 v37, v2, s34, -v37
	v_fmac_f32_e32 v37, 0x3377d1cf, v2
	v_fmac_f32_e32 v37, 0x3f317217, v2
	v_cmp_lt_f32_e64 s[0:1], |v2|, s37
	s_nop 1
	v_cndmask_b32_e64 v2, v2, v37, s[0:1]
	v_cndmask_b32_e32 v37, 0, v230, vcc
	v_sub_f32_e32 v37, v2, v37
	v_max_f32_e32 v2, v38, v38
	v_max_f32_e32 v2, 0xda24260, v2
	v_sub_f32_e32 v38, 1.0, v38
	v_fmac_f32_e32 v2, v40, v38
	v_cmp_gt_f32_e32 vcc, s19, v2
	v_mul_f32_e32 v40, 0xbfb8aa3b, v23
	v_exp_f32_e32 v40, v40
	v_cndmask_b32_e64 v38, 0, 32, vcc
	v_ldexp_f32 v2, v2, v38
	v_log_f32_e32 v2, v2
	v_add_f32_e32 v40, 1.0, v40
	v_rcp_f32_e32 v40, v40
	v_mul_f32_e32 v38, 0x3f317217, v2
	v_fma_f32 v38, v2, s34, -v38
	v_fmac_f32_e32 v38, 0x3377d1cf, v2
	v_fmac_f32_e32 v38, 0x3f317217, v2
	v_cmp_lt_f32_e64 s[0:1], |v2|, s37
	s_nop 1
	v_cndmask_b32_e64 v2, v2, v38, s[0:1]
	v_cndmask_b32_e32 v38, 0, v230, vcc
	v_sub_f32_e32 v38, v2, v38
	v_max_f32_e32 v2, v39, v39
	v_max_f32_e32 v2, 0xda24260, v2
	v_sub_f32_e32 v39, 1.0, v39
	v_fmac_f32_e32 v2, v40, v39
	v_cmp_gt_f32_e32 vcc, s19, v2
	s_nop 1
	v_cndmask_b32_e64 v39, 0, 32, vcc
	v_ldexp_f32 v2, v2, v39
	v_log_f32_e32 v2, v2
	s_nop 0
	v_mul_f32_e32 v39, 0x3f317217, v2
	v_fma_f32 v39, v2, s34, -v39
	v_fmac_f32_e32 v39, 0x3377d1cf, v2
	v_fmac_f32_e32 v39, 0x3f317217, v2
	v_cmp_lt_f32_e64 s[0:1], |v2|, s37
	s_nop 1
	v_cndmask_b32_e64 v2, v2, v39, s[0:1]
	v_cndmask_b32_e32 v39, 0, v230, vcc
	v_sub_f32_e32 v39, v2, v39
	s_mov_b64 s[0:1], 0

.LBB0_401:
	s_andn2_b64 vcc, exec, s[6:7]
	s_cbranch_vccnz .LBB0_404
	s_andn2_b64 vcc, exec, s[10:11]
	s_cbranch_vccnz .LBB0_467
	v_lshlrev_b32_e32 v2, 2, v77
	s_waitcnt vmcnt(0)
	v_mov_b32_e32 v20, v116
	v_mov_b32_e32 v21, v117
	v_mov_b32_e32 v22, v118
	v_mov_b32_e32 v23, v119
	v_mul_f32_e32 v24, 0xbfb8aa3b, v16
	v_exp_f32_e32 v24, v24
	s_mov_b32 s6, 0x3f317217
	v_add_f32_e32 v24, 1.0, v24
	v_rcp_f32_e32 v24, v24
	s_waitcnt vmcnt(0)
	v_max_f32_e32 v2, v20, v20
	v_max_f32_e32 v2, 0xda24260, v2
	v_sub_f32_e32 v20, 1.0, v20
	v_fmac_f32_e32 v2, v24, v20
	v_cmp_gt_f32_e32 vcc, s19, v2
	v_mul_f32_e32 v24, 0xbfb8aa3b, v17
	v_exp_f32_e32 v24, v24
	v_cndmask_b32_e64 v20, 0, 32, vcc
	v_ldexp_f32 v2, v2, v20
	v_log_f32_e32 v2, v2
	v_add_f32_e32 v24, 1.0, v24
	v_rcp_f32_e32 v24, v24
	v_mul_f32_e32 v20, 0x3f317217, v2
	v_fma_f32 v20, v2, s6, -v20
	v_fmac_f32_e32 v20, 0x3377d1cf, v2
	v_fmac_f32_e32 v20, 0x3f317217, v2
	v_cmp_lt_f32_e64 s[0:1], |v2|, s37
	s_nop 1
	v_cndmask_b32_e64 v2, v2, v20, s[0:1]
	v_cndmask_b32_e32 v20, 0, v230, vcc
	v_sub_f32_e32 v20, v2, v20
	v_max_f32_e32 v2, v21, v21
	v_max_f32_e32 v2, 0xda24260, v2
	v_sub_f32_e32 v21, 1.0, v21
	v_fmac_f32_e32 v2, v24, v21
	v_cmp_gt_f32_e32 vcc, s19, v2
	v_mul_f32_e32 v24, 0xbfb8aa3b, v18
	v_exp_f32_e32 v24, v24
	v_cndmask_b32_e64 v21, 0, 32, vcc
	v_ldexp_f32 v2, v2, v21
	v_log_f32_e32 v2, v2
	v_add_f32_e32 v24, 1.0, v24
	v_rcp_f32_e32 v24, v24
	v_mul_f32_e32 v21, 0x3f317217, v2
	v_fma_f32 v21, v2, s6, -v21
	v_fmac_f32_e32 v21, 0x3377d1cf, v2
	v_fmac_f32_e32 v21, 0x3f317217, v2
	v_cmp_lt_f32_e64 s[0:1], |v2|, s37
	s_nop 1
	v_cndmask_b32_e64 v2, v2, v21, s[0:1]
	v_cndmask_b32_e32 v21, 0, v230, vcc
	v_sub_f32_e32 v21, v2, v21
	v_max_f32_e32 v2, v22, v22
	v_max_f32_e32 v2, 0xda24260, v2
	v_sub_f32_e32 v22, 1.0, v22
	v_fmac_f32_e32 v2, v24, v22
	v_cmp_gt_f32_e32 vcc, s19, v2
	v_mul_f32_e32 v24, 0xbfb8aa3b, v19
	v_exp_f32_e32 v24, v24
	v_cndmask_b32_e64 v22, 0, 32, vcc
	v_ldexp_f32 v2, v2, v22
	v_log_f32_e32 v2, v2
	v_add_f32_e32 v24, 1.0, v24
	v_rcp_f32_e32 v24, v24
	v_mul_f32_e32 v22, 0x3f317217, v2
	v_fma_f32 v22, v2, s6, -v22
	v_fmac_f32_e32 v22, 0x3377d1cf, v2
	v_fmac_f32_e32 v22, 0x3f317217, v2
	v_cmp_lt_f32_e64 s[0:1], |v2|, s37
	s_nop 1
	v_cndmask_b32_e64 v2, v2, v22, s[0:1]
	v_cndmask_b32_e32 v22, 0, v230, vcc
	v_sub_f32_e32 v22, v2, v22
	v_max_f32_e32 v2, v23, v23
	v_max_f32_e32 v2, 0xda24260, v2
	v_sub_f32_e32 v23, 1.0, v23
	v_fmac_f32_e32 v2, v24, v23
	v_cmp_gt_f32_e32 vcc, s19, v2
	s_nop 1
	v_cndmask_b32_e64 v23, 0, 32, vcc
	v_ldexp_f32 v2, v2, v23
	v_log_f32_e32 v2, v2
	s_nop 0
	v_mul_f32_e32 v23, 0x3f317217, v2
	v_fma_f32 v23, v2, s6, -v23
	v_fmac_f32_e32 v23, 0x3377d1cf, v2
	v_fmac_f32_e32 v23, 0x3f317217, v2
	v_cmp_lt_f32_e64 s[0:1], |v2|, s37
	s_nop 1
	v_cndmask_b32_e64 v2, v2, v23, s[0:1]
	v_cndmask_b32_e32 v23, 0, v230, vcc
	v_sub_f32_e32 v23, v2, v23
	s_mov_b64 s[0:1], 0

.LBB0_416:
	s_andn2_b64 vcc, exec, s[6:7]
	s_cbranch_vccnz .LBB0_419
	s_andn2_b64 vcc, exec, s[10:11]
	s_cbranch_vccnz .LBB0_468
	v_lshlrev_b32_e32 v2, 2, v77
	s_waitcnt vmcnt(0)
	v_mov_b32_e32 v20, v120
	v_mov_b32_e32 v21, v121
	v_mov_b32_e32 v22, v122
	v_mov_b32_e32 v23, v123
	v_mul_f32_e32 v24, 0xbfb8aa3b, v12
	v_exp_f32_e32 v24, v24
	s_mov_b32 s6, 0x3f317217
	v_add_f32_e32 v24, 1.0, v24
	v_rcp_f32_e32 v24, v24
	s_waitcnt vmcnt(0)
	v_max_f32_e32 v2, v20, v20
	v_max_f32_e32 v2, 0xda24260, v2
	v_sub_f32_e32 v20, 1.0, v20
	v_fmac_f32_e32 v2, v24, v20
	v_cmp_gt_f32_e32 vcc, s19, v2
	v_mul_f32_e32 v24, 0xbfb8aa3b, v13
	v_exp_f32_e32 v24, v24
	v_cndmask_b32_e64 v20, 0, 32, vcc
	v_ldexp_f32 v2, v2, v20
	v_log_f32_e32 v2, v2
	v_add_f32_e32 v24, 1.0, v24
	v_rcp_f32_e32 v24, v24
	v_mul_f32_e32 v20, 0x3f317217, v2
	v_fma_f32 v20, v2, s6, -v20
	v_fmac_f32_e32 v20, 0x3377d1cf, v2
	v_fmac_f32_e32 v20, 0x3f317217, v2
	v_cmp_lt_f32_e64 s[0:1], |v2|, s37
	s_nop 1
	v_cndmask_b32_e64 v2, v2, v20, s[0:1]
	v_cndmask_b32_e32 v20, 0, v230, vcc
	v_sub_f32_e32 v20, v2, v20
	v_max_f32_e32 v2, v21, v21
	v_max_f32_e32 v2, 0xda24260, v2
	v_sub_f32_e32 v21, 1.0, v21
	v_fmac_f32_e32 v2, v24, v21
	v_cmp_gt_f32_e32 vcc, s19, v2
	v_mul_f32_e32 v24, 0xbfb8aa3b, v14
	v_exp_f32_e32 v24, v24
	v_cndmask_b32_e64 v21, 0, 32, vcc
	v_ldexp_f32 v2, v2, v21
	v_log_f32_e32 v2, v2
	v_add_f32_e32 v24, 1.0, v24
	v_rcp_f32_e32 v24, v24
	v_mul_f32_e32 v21, 0x3f317217, v2
	v_fma_f32 v21, v2, s6, -v21
	v_fmac_f32_e32 v21, 0x3377d1cf, v2
	v_fmac_f32_e32 v21, 0x3f317217, v2
	v_cmp_lt_f32_e64 s[0:1], |v2|, s37
	s_nop 1
	v_cndmask_b32_e64 v2, v2, v21, s[0:1]
	v_cndmask_b32_e32 v21, 0, v230, vcc
	v_sub_f32_e32 v21, v2, v21
	v_max_f32_e32 v2, v22, v22
	v_max_f32_e32 v2, 0xda24260, v2
	v_sub_f32_e32 v22, 1.0, v22
	v_fmac_f32_e32 v2, v24, v22
	v_cmp_gt_f32_e32 vcc, s19, v2
	v_mul_f32_e32 v24, 0xbfb8aa3b, v15
	v_exp_f32_e32 v24, v24
	v_cndmask_b32_e64 v22, 0, 32, vcc
	v_ldexp_f32 v2, v2, v22
	v_log_f32_e32 v2, v2
	v_add_f32_e32 v24, 1.0, v24
	v_rcp_f32_e32 v24, v24
	v_mul_f32_e32 v22, 0x3f317217, v2
	v_fma_f32 v22, v2, s6, -v22
	v_fmac_f32_e32 v22, 0x3377d1cf, v2
	v_fmac_f32_e32 v22, 0x3f317217, v2
	v_cmp_lt_f32_e64 s[0:1], |v2|, s37
	s_nop 1
	v_cndmask_b32_e64 v2, v2, v22, s[0:1]
	v_cndmask_b32_e32 v22, 0, v230, vcc
	v_sub_f32_e32 v22, v2, v22
	v_max_f32_e32 v2, v23, v23
	v_max_f32_e32 v2, 0xda24260, v2
	v_sub_f32_e32 v23, 1.0, v23
	v_fmac_f32_e32 v2, v24, v23
	v_cmp_gt_f32_e32 vcc, s19, v2
	s_nop 1
	v_cndmask_b32_e64 v23, 0, 32, vcc
	v_ldexp_f32 v2, v2, v23
	v_log_f32_e32 v2, v2
	s_nop 0
	v_mul_f32_e32 v23, 0x3f317217, v2
	v_fma_f32 v23, v2, s6, -v23
	v_fmac_f32_e32 v23, 0x3377d1cf, v2
	v_fmac_f32_e32 v23, 0x3f317217, v2
	v_cmp_lt_f32_e64 s[0:1], |v2|, s37
	s_nop 1
	v_cndmask_b32_e64 v2, v2, v23, s[0:1]
	v_cndmask_b32_e32 v23, 0, v230, vcc
	v_sub_f32_e32 v23, v2, v23
	s_mov_b64 s[0:1], 0

.LBB0_431:
	s_andn2_b64 vcc, exec, s[6:7]
	s_cbranch_vccnz .LBB0_434
	s_andn2_b64 vcc, exec, s[10:11]
	s_cbranch_vccnz .LBB0_469
	v_lshlrev_b32_e32 v2, 2, v77
	s_waitcnt vmcnt(0)
	v_mov_b32_e32 v20, v124
	v_mov_b32_e32 v21, v125
	v_mov_b32_e32 v22, v126
	v_mov_b32_e32 v23, v127
	v_mul_f32_e32 v24, 0xbfb8aa3b, v4
	v_exp_f32_e32 v24, v24
	s_mov_b32 s6, 0x3f317217
	v_add_f32_e32 v24, 1.0, v24
	v_rcp_f32_e32 v24, v24
	s_waitcnt vmcnt(0)
	v_max_f32_e32 v2, v20, v20
	v_max_f32_e32 v2, 0xda24260, v2
	v_sub_f32_e32 v20, 1.0, v20
	v_fmac_f32_e32 v2, v24, v20
	v_cmp_gt_f32_e32 vcc, s19, v2
	v_mul_f32_e32 v24, 0xbfb8aa3b, v5
	v_exp_f32_e32 v24, v24
	v_cndmask_b32_e64 v20, 0, 32, vcc
	v_ldexp_f32 v2, v2, v20
	v_log_f32_e32 v2, v2
	v_add_f32_e32 v24, 1.0, v24
	v_rcp_f32_e32 v24, v24
	v_mul_f32_e32 v20, 0x3f317217, v2
	v_fma_f32 v20, v2, s6, -v20
	v_fmac_f32_e32 v20, 0x3377d1cf, v2
	v_fmac_f32_e32 v20, 0x3f317217, v2
	v_cmp_lt_f32_e64 s[0:1], |v2|, s37
	s_nop 1
	v_cndmask_b32_e64 v2, v2, v20, s[0:1]
	v_cndmask_b32_e32 v20, 0, v230, vcc
	v_sub_f32_e32 v20, v2, v20
	v_max_f32_e32 v2, v21, v21
	v_max_f32_e32 v2, 0xda24260, v2
	v_sub_f32_e32 v21, 1.0, v21
	v_fmac_f32_e32 v2, v24, v21
	v_cmp_gt_f32_e32 vcc, s19, v2
	v_mul_f32_e32 v24, 0xbfb8aa3b, v6
	v_exp_f32_e32 v24, v24
	v_cndmask_b32_e64 v21, 0, 32, vcc
	v_ldexp_f32 v2, v2, v21
	v_log_f32_e32 v2, v2
	v_add_f32_e32 v24, 1.0, v24
	v_rcp_f32_e32 v24, v24
	v_mul_f32_e32 v21, 0x3f317217, v2
	v_fma_f32 v21, v2, s6, -v21
	v_fmac_f32_e32 v21, 0x3377d1cf, v2
	v_fmac_f32_e32 v21, 0x3f317217, v2
	v_cmp_lt_f32_e64 s[0:1], |v2|, s37
	s_nop 1
	v_cndmask_b32_e64 v2, v2, v21, s[0:1]
	v_cndmask_b32_e32 v21, 0, v230, vcc
	v_sub_f32_e32 v21, v2, v21
	v_max_f32_e32 v2, v22, v22
	v_max_f32_e32 v2, 0xda24260, v2
	v_sub_f32_e32 v22, 1.0, v22
	v_fmac_f32_e32 v2, v24, v22
	v_cmp_gt_f32_e32 vcc, s19, v2
	v_mul_f32_e32 v24, 0xbfb8aa3b, v7
	v_exp_f32_e32 v24, v24
	v_cndmask_b32_e64 v22, 0, 32, vcc
	v_ldexp_f32 v2, v2, v22
	v_log_f32_e32 v2, v2
	v_add_f32_e32 v24, 1.0, v24
	v_rcp_f32_e32 v24, v24
	v_mul_f32_e32 v22, 0x3f317217, v2
	v_fma_f32 v22, v2, s6, -v22
	v_fmac_f32_e32 v22, 0x3377d1cf, v2
	v_fmac_f32_e32 v22, 0x3f317217, v2
	v_cmp_lt_f32_e64 s[0:1], |v2|, s37
	s_nop 1
	v_cndmask_b32_e64 v2, v2, v22, s[0:1]
	v_cndmask_b32_e32 v22, 0, v230, vcc
	v_sub_f32_e32 v22, v2, v22
	v_max_f32_e32 v2, v23, v23
	v_max_f32_e32 v2, 0xda24260, v2
	v_sub_f32_e32 v23, 1.0, v23
	v_fmac_f32_e32 v2, v24, v23
	v_cmp_gt_f32_e32 vcc, s19, v2
	s_nop 1
	v_cndmask_b32_e64 v23, 0, 32, vcc
	v_ldexp_f32 v2, v2, v23
	v_log_f32_e32 v2, v2
	s_nop 0
	v_mul_f32_e32 v23, 0x3f317217, v2
	v_fma_f32 v23, v2, s6, -v23
	v_fmac_f32_e32 v23, 0x3377d1cf, v2
	v_fmac_f32_e32 v23, 0x3f317217, v2
	v_cmp_lt_f32_e64 s[0:1], |v2|, s37
	s_nop 1
	v_cndmask_b32_e64 v2, v2, v23, s[0:1]
	v_cndmask_b32_e32 v23, 0, v230, vcc
	v_sub_f32_e32 v23, v2, v23
	s_mov_b64 s[0:1], 0

.LBB0_446:
	s_andn2_b64 vcc, exec, s[4:5]
	s_cbranch_vccnz .LBB0_449
	s_andn2_b64 vcc, exec, s[10:11]
	s_cbranch_vccnz .LBB0_470
	v_lshlrev_b32_e32 v2, 2, v77
	s_waitcnt vmcnt(0)
	v_mov_b32_e32 v20, v128
	v_mov_b32_e32 v21, v129
	v_mov_b32_e32 v22, v130
	v_mov_b32_e32 v23, v131
	v_mul_f32_e32 v24, 0xbfb8aa3b, v8
	v_exp_f32_e32 v24, v24
	s_mov_b32 s4, 0x3f317217
	v_add_f32_e32 v24, 1.0, v24
	v_rcp_f32_e32 v24, v24
	s_waitcnt vmcnt(0)
	v_max_f32_e32 v2, v20, v20
	v_max_f32_e32 v2, 0xda24260, v2
	v_sub_f32_e32 v20, 1.0, v20
	v_fmac_f32_e32 v2, v24, v20
	v_cmp_gt_f32_e32 vcc, s19, v2
	v_mul_f32_e32 v24, 0xbfb8aa3b, v9
	v_exp_f32_e32 v24, v24
	v_cndmask_b32_e64 v20, 0, 32, vcc
	v_ldexp_f32 v2, v2, v20
	v_log_f32_e32 v2, v2
	v_add_f32_e32 v24, 1.0, v24
	v_rcp_f32_e32 v24, v24
	v_mul_f32_e32 v20, 0x3f317217, v2
	v_fma_f32 v20, v2, s4, -v20
	v_fmac_f32_e32 v20, 0x3377d1cf, v2
	v_fmac_f32_e32 v20, 0x3f317217, v2
	v_cmp_lt_f32_e64 s[0:1], |v2|, s37
	s_nop 1
	v_cndmask_b32_e64 v2, v2, v20, s[0:1]
	v_cndmask_b32_e32 v20, 0, v230, vcc
	v_sub_f32_e32 v20, v2, v20
	v_max_f32_e32 v2, v21, v21
	v_max_f32_e32 v2, 0xda24260, v2
	v_sub_f32_e32 v21, 1.0, v21
	v_fmac_f32_e32 v2, v24, v21
	v_cmp_gt_f32_e32 vcc, s19, v2
	v_mul_f32_e32 v24, 0xbfb8aa3b, v10
	v_exp_f32_e32 v24, v24
	v_cndmask_b32_e64 v21, 0, 32, vcc
	v_ldexp_f32 v2, v2, v21
	v_log_f32_e32 v2, v2
	v_add_f32_e32 v24, 1.0, v24
	v_rcp_f32_e32 v24, v24
	v_mul_f32_e32 v21, 0x3f317217, v2
	v_fma_f32 v21, v2, s4, -v21
	v_fmac_f32_e32 v21, 0x3377d1cf, v2
	v_fmac_f32_e32 v21, 0x3f317217, v2
	v_cmp_lt_f32_e64 s[0:1], |v2|, s37
	s_nop 1
	v_cndmask_b32_e64 v2, v2, v21, s[0:1]
	v_cndmask_b32_e32 v21, 0, v230, vcc
	v_sub_f32_e32 v21, v2, v21
	v_max_f32_e32 v2, v22, v22
	v_max_f32_e32 v2, 0xda24260, v2
	v_sub_f32_e32 v22, 1.0, v22
	v_fmac_f32_e32 v2, v24, v22
	v_cmp_gt_f32_e32 vcc, s19, v2
	v_mul_f32_e32 v24, 0xbfb8aa3b, v11
	v_exp_f32_e32 v24, v24
	v_cndmask_b32_e64 v22, 0, 32, vcc
	v_ldexp_f32 v2, v2, v22
	v_log_f32_e32 v2, v2
	v_add_f32_e32 v24, 1.0, v24
	v_rcp_f32_e32 v24, v24
	v_mul_f32_e32 v22, 0x3f317217, v2
	v_fma_f32 v22, v2, s4, -v22
	v_fmac_f32_e32 v22, 0x3377d1cf, v2
	v_fmac_f32_e32 v22, 0x3f317217, v2
	v_cmp_lt_f32_e64 s[0:1], |v2|, s37
	s_nop 1
	v_cndmask_b32_e64 v2, v2, v22, s[0:1]
	v_cndmask_b32_e32 v22, 0, v230, vcc
	v_sub_f32_e32 v22, v2, v22
	v_max_f32_e32 v2, v23, v23
	v_max_f32_e32 v2, 0xda24260, v2
	v_sub_f32_e32 v23, 1.0, v23
	v_fmac_f32_e32 v2, v24, v23
	v_cmp_gt_f32_e32 vcc, s19, v2
	s_nop 1
	v_cndmask_b32_e64 v23, 0, 32, vcc
	v_ldexp_f32 v2, v2, v23
	v_log_f32_e32 v2, v2
	s_nop 0
	v_mul_f32_e32 v23, 0x3f317217, v2
	v_fma_f32 v23, v2, s4, -v23
	v_fmac_f32_e32 v23, 0x3377d1cf, v2
	v_fmac_f32_e32 v23, 0x3f317217, v2
	v_cmp_lt_f32_e64 s[0:1], |v2|, s37
	s_nop 1
	v_cndmask_b32_e64 v2, v2, v23, s[0:1]
	v_cndmask_b32_e32 v23, 0, v230, vcc
	v_sub_f32_e32 v23, v2, v23
	s_mov_b64 s[0:1], 0
